# stack: finalize row loads batched + G1 q/k gain loads batched (one wait instead of four) + G1/G3 epilogue no longer drains the next unit's LDS-DMA prefetch + attention inter-branch barriers keep only
# speedup vs baseline: 1.0128x; 1.0009x over previous
.LBB0_155:
	v_cndmask_b32_e64 v154, 0, 1, s[38:39]
	v_cmp_ne_u32_e64 s[40:41], 1, v154
	s_andn2_b64 vcc, exec, s[38:39]
	v_readlane_b32 s87, v254, 61
	v_readlane_b32 s80, v254, 62
	s_cbranch_vccnz .LBB0_157
	s_lshl_b64 s[38:39], s[58:59], 14
	v_lshl_add_u64 v[6:7], v[146:147], 0, s[38:39]
	global_load_dwordx4 v[2:5], v[6:7], off offset:16
	s_nop 0
	global_load_dwordx4 v[6:9], v[6:7], off

.LBB0_667:
	v_cndmask_b32_e64 v154, 0, 1, s[40:41]
	v_cmp_ne_u32_e64 s[38:39], 1, v154
	s_andn2_b64 vcc, exec, s[40:41]
	v_readlane_b32 s87, v254, 61
	s_cbranch_vccnz .LBB0_669
	s_lshl_b64 s[40:41], s[60:61], 14
	v_lshl_add_u64 v[6:7], v[148:149], 0, s[40:41]
	global_load_dwordx4 v[2:5], v[6:7], off offset:16
	s_nop 0
	global_load_dwordx4 v[6:9], v[6:7], off
.LBB0_669:
	s_cmp_lt_i32 s83, 4
	s_cselect_b64 s[40:41], -1, 0
	s_cmp_lt_i32 s83, 2
	s_cselect_b64 vcc, -1, 0
	s_and_b64 s[42:43], vcc, exec
	s_cselect_b32 s42, s24, s26
	s_cselect_b32 s43, s25, s27
	s_add_u32 s42, s42, s54
	v_cndmask_b32_e32 v170, 1.0, v227, vcc
	s_addc_u32 s43, s43, s55
	v_mov_b32_e32 v171, v170
	v_lshl_add_u64 v[172:173], v[146:147], 2, s[42:43]
	v_mov_b32_e32 v154, 1.0
	v_mov_b32_e32 v155, 1.0
	v_mov_b32_e32 v156, 1.0
	v_mov_b32_e32 v157, 1.0
	v_mov_b32_e32 v158, 1.0
	v_mov_b32_e32 v159, 1.0
	v_mov_b32_e32 v160, 1.0
	v_mov_b32_e32 v161, 1.0
	v_mov_b32_e32 v162, 1.0
	v_mov_b32_e32 v163, 1.0
	v_mov_b32_e32 v164, 1.0
	v_mov_b32_e32 v165, 1.0
	v_mov_b32_e32 v166, 1.0
	v_mov_b32_e32 v167, 1.0
	v_mov_b32_e32 v168, 1.0
	v_mov_b32_e32 v169, 1.0
	v_readlane_b32 s94, v254, 59
	v_readlane_b32 s95, v254, 60
	s_andn2_b64 vcc, exec, s[40:41]
	s_cbranch_vccnz .LBB0_677
	global_load_dwordx4 v[200:203], v[172:173], off
	global_load_dwordx4 v[204:207], v[172:173], off offset:16
	global_load_dwordx4 v[208:211], v[172:173], off offset:128
	global_load_dwordx4 v[212:215], v[172:173], off offset:144
	s_waitcnt vmcnt(0)
	v_pk_mul_f32 v[156:157], v[170:171], v[200:201]
	v_pk_mul_f32 v[158:159], v[170:171], v[202:203]
	v_pk_mul_f32 v[154:155], v[170:171], v[204:205]
	v_pk_mul_f32 v[160:161], v[170:171], v[206:207]
	v_pk_mul_f32 v[164:165], v[170:171], v[208:209]
	v_pk_mul_f32 v[166:167], v[170:171], v[210:211]
	v_pk_mul_f32 v[162:163], v[170:171], v[212:213]
	v_pk_mul_f32 v[168:169], v[170:171], v[214:215]
